# sunk re-stagger rendezvous; lagging half delays its accumulator zeroing ~320 cycles so it follows the leading half's
# baseline (speedup 1.0000x reference)
.LBB0_245:
	s_ashr_i32 s69, s68, 31
	s_lshl_b64 s[56:57], s[68:69], 20
	s_add_u32 s33, s14, s56
	s_addc_u32 s48, s15, s57
	s_ashr_i32 s75, s74, 31
	s_lshl_b64 s[56:57], s[74:75], 7
	s_add_u32 s84, s33, s56
	s_addc_u32 s85, s48, s57
	s_and_b64 s[76:77], s[90:91], exec
	s_cselect_b32 s69, s85, s1
	s_cselect_b32 s75, s84, s0
	s_ashr_i32 s73, s72, 31
	s_lshl_b64 s[76:77], s[72:73], 20
	s_add_u32 s33, s9, s76
	s_addc_u32 s48, s23, s77
	s_add_u32 s86, s33, s56
	s_addc_u32 s87, s48, s57
	s_and_b64 s[56:57], s[90:91], exec
	s_cselect_b32 s73, s87, s89
	s_cselect_b32 vcc_lo, s86, s88
	s_add_i32 vcc_hi, s55, -2
	s_add_u32 s0, s0, 0x80080
	s_addc_u32 s1, s1, 0
	s_add_u32 s56, s88, 0x100
	s_addc_u32 s57, s89, 0
	s_mov_b32 s88, 0
	s_cmp_eq_u32 s100, 0
	s_cbranch_scc1 .Lrd1
	s_nop 15
	s_nop 15
	s_nop 15
	s_nop 15
	s_nop 15
.Lrd1:
	v_mov_b64_e32 v[4:5], 0
	v_mov_b64_e32 v[6:7], 0
	v_mov_b64_e32 v[8:9], 0
	v_mov_b64_e32 v[10:11], 0
	v_mov_b64_e32 v[12:13], 0
	v_mov_b64_e32 v[14:15], 0
	v_mov_b64_e32 v[16:17], 0
	v_mov_b64_e32 v[18:19], 0
	v_mov_b64_e32 v[20:21], 0
	v_mov_b64_e32 v[22:23], 0
	v_mov_b64_e32 v[24:25], 0
	v_mov_b64_e32 v[26:27], 0
	v_mov_b64_e32 v[28:29], 0
	v_mov_b64_e32 v[30:31], 0
	v_mov_b64_e32 v[32:33], 0
	v_mov_b64_e32 v[34:35], 0
	v_mov_b64_e32 v[36:37], 0
	v_mov_b64_e32 v[38:39], 0
	v_mov_b64_e32 v[40:41], 0
	v_mov_b64_e32 v[42:43], 0
	v_mov_b64_e32 v[44:45], 0
	v_mov_b64_e32 v[46:47], 0
	v_mov_b64_e32 v[48:49], 0
	v_mov_b64_e32 v[50:51], 0
	v_mov_b64_e32 v[52:53], 0
	v_mov_b64_e32 v[54:55], 0
	v_mov_b64_e32 v[56:57], 0
	v_mov_b64_e32 v[58:59], 0
	v_mov_b64_e32 v[60:61], 0
	v_mov_b64_e32 v[62:63], 0
	v_mov_b64_e32 v[64:65], 0
	v_mov_b64_e32 v[66:67], 0
	v_mov_b64_e32 v[68:69], 0
	v_mov_b64_e32 v[70:71], 0
	v_mov_b64_e32 v[72:73], 0
	v_mov_b64_e32 v[74:75], 0
	v_mov_b64_e32 v[76:77], 0
	v_mov_b64_e32 v[78:79], 0
	v_mov_b64_e32 v[80:81], 0
	v_mov_b64_e32 v[82:83], 0
	v_mov_b64_e32 v[84:85], 0
	v_mov_b64_e32 v[86:87], 0
	v_mov_b64_e32 v[88:89], 0
	v_mov_b64_e32 v[90:91], 0
	v_mov_b64_e32 v[92:93], 0
	v_mov_b64_e32 v[94:95], 0
	v_mov_b64_e32 v[96:97], 0
	v_mov_b64_e32 v[98:99], 0
	v_mov_b64_e32 v[100:101], 0
	v_mov_b64_e32 v[102:103], 0
	v_mov_b64_e32 v[104:105], 0
	v_mov_b64_e32 v[106:107], 0
	v_mov_b64_e32 v[108:109], 0
	v_mov_b64_e32 v[110:111], 0
	v_mov_b64_e32 v[112:113], 0
	v_mov_b64_e32 v[114:115], 0
	v_mov_b64_e32 v[116:117], 0
	v_mov_b64_e32 v[118:119], 0
	v_mov_b64_e32 v[120:121], 0
	v_mov_b64_e32 v[122:123], 0
	v_mov_b64_e32 v[124:125], 0
	v_mov_b64_e32 v[126:127], 0
	v_mov_b64_e32 v[128:129], 0
	v_mov_b64_e32 v[130:131], 0
	v_add_u32_e32 v246, 0x10000, v1
	v_add_u32_e32 v247, 0x14000, v1
	v_add_u32_e32 v248, 0x18000, v1
	v_add_u32_e32 v249, 0x1c000, v1
	s_cmp_eq_u32 s100, 0
	s_cbranch_scc1 .Lrs1
	s_barrier
	s_mov_b32 s100, 0

.LBB0_520:
	s_add_i32 s9, s64, -2
	s_add_u32 s74, s74, 0x80080
	s_addc_u32 s75, s75, 0
	s_add_u32 s23, s84, 0x100
	s_addc_u32 s35, s85, 0
	s_mov_b32 s54, 0
	s_cmp_eq_u32 s100, 0
	s_cbranch_scc1 .Lrd3
	s_nop 15
	s_nop 15
	s_nop 15
	s_nop 15
	s_nop 15
.Lrd3:
	v_mov_b64_e32 v[4:5], 0
	v_mov_b64_e32 v[6:7], 0
	v_mov_b64_e32 v[8:9], 0
	v_mov_b64_e32 v[10:11], 0
	v_mov_b64_e32 v[12:13], 0
	v_mov_b64_e32 v[14:15], 0
	v_mov_b64_e32 v[16:17], 0
	v_mov_b64_e32 v[18:19], 0
	v_mov_b64_e32 v[20:21], 0
	v_mov_b64_e32 v[22:23], 0
	v_mov_b64_e32 v[24:25], 0
	v_mov_b64_e32 v[26:27], 0
	v_mov_b64_e32 v[28:29], 0
	v_mov_b64_e32 v[30:31], 0
	v_mov_b64_e32 v[32:33], 0
	v_mov_b64_e32 v[34:35], 0
	v_mov_b64_e32 v[36:37], 0
	v_mov_b64_e32 v[38:39], 0
	v_mov_b64_e32 v[40:41], 0
	v_mov_b64_e32 v[42:43], 0
	v_mov_b64_e32 v[44:45], 0
	v_mov_b64_e32 v[46:47], 0
	v_mov_b64_e32 v[48:49], 0
	v_mov_b64_e32 v[50:51], 0
	v_mov_b64_e32 v[52:53], 0
	v_mov_b64_e32 v[54:55], 0
	v_mov_b64_e32 v[56:57], 0
	v_mov_b64_e32 v[58:59], 0
	v_mov_b64_e32 v[60:61], 0
	v_mov_b64_e32 v[62:63], 0
	v_mov_b64_e32 v[64:65], 0
	v_mov_b64_e32 v[66:67], 0
	v_mov_b64_e32 v[68:69], 0
	v_mov_b64_e32 v[70:71], 0
	v_mov_b64_e32 v[72:73], 0
	v_mov_b64_e32 v[74:75], 0
	v_mov_b64_e32 v[76:77], 0
	v_mov_b64_e32 v[78:79], 0
	v_mov_b64_e32 v[80:81], 0
	v_mov_b64_e32 v[82:83], 0
	v_mov_b64_e32 v[84:85], 0
	v_mov_b64_e32 v[86:87], 0
	v_mov_b64_e32 v[88:89], 0
	v_mov_b64_e32 v[90:91], 0
	v_mov_b64_e32 v[92:93], 0
	v_mov_b64_e32 v[94:95], 0
	v_mov_b64_e32 v[96:97], 0
	v_mov_b64_e32 v[98:99], 0
	v_mov_b64_e32 v[100:101], 0
	v_mov_b64_e32 v[102:103], 0
	v_mov_b64_e32 v[104:105], 0
	v_mov_b64_e32 v[106:107], 0
	v_mov_b64_e32 v[108:109], 0
	v_mov_b64_e32 v[110:111], 0
	v_mov_b64_e32 v[112:113], 0
	v_mov_b64_e32 v[114:115], 0
	v_mov_b64_e32 v[116:117], 0
	v_mov_b64_e32 v[118:119], 0
	v_mov_b64_e32 v[120:121], 0
	v_mov_b64_e32 v[122:123], 0
	v_mov_b64_e32 v[124:125], 0
	v_mov_b64_e32 v[126:127], 0
	v_mov_b64_e32 v[128:129], 0
	v_mov_b64_e32 v[130:131], 0
	v_add_u32_e32 v246, 0x10000, v142
	v_add_u32_e32 v247, 0x14000, v142
	v_add_u32_e32 v248, 0x18000, v142
	v_add_u32_e32 v249, 0x1c000, v142
	s_cmp_eq_u32 s100, 0
	s_cbranch_scc1 .Lrs3
	s_barrier
	s_mov_b32 s100, 0

.LBB0_693:
	s_ashr_i32 s75, s74, 31
	s_lshl_b64 s[16:17], s[74:75], 20
	s_add_u32 s84, s14, s16
	s_addc_u32 s85, s15, s17
	s_and_b64 s[16:17], s[36:37], exec
	s_cselect_b32 s16, s85, s89
	s_cselect_b32 s17, s84, s88
	s_ashr_i32 s73, s72, 31
	s_lshl_b64 s[50:51], s[72:73], 20
	s_add_u32 s86, s23, s50
	s_addc_u32 s87, s29, s51
	s_and_b64 s[50:51], s[36:37], exec
	s_cselect_b32 s50, s87, s91
	s_cselect_b32 s51, s86, s90
	s_add_u32 s88, s88, 0x80080
	s_addc_u32 s89, s89, 0
	s_add_u32 s54, s90, 0x100
	s_addc_u32 s55, s91, 0
	s_mov_b32 s56, -2
	s_cmp_eq_u32 s100, 0
	s_cbranch_scc1 .Lrd5
	s_nop 15
	s_nop 15
	s_nop 15
	s_nop 15
	s_nop 15
.Lrd5:
	v_mov_b64_e32 v[4:5], 0
	v_mov_b64_e32 v[6:7], 0
	v_mov_b64_e32 v[8:9], 0
	v_mov_b64_e32 v[10:11], 0
	v_mov_b64_e32 v[12:13], 0
	v_mov_b64_e32 v[14:15], 0
	v_mov_b64_e32 v[16:17], 0
	v_mov_b64_e32 v[18:19], 0
	v_mov_b64_e32 v[20:21], 0
	v_mov_b64_e32 v[22:23], 0
	v_mov_b64_e32 v[24:25], 0
	v_mov_b64_e32 v[26:27], 0
	v_mov_b64_e32 v[28:29], 0
	v_mov_b64_e32 v[30:31], 0
	v_mov_b64_e32 v[32:33], 0
	v_mov_b64_e32 v[34:35], 0
	v_mov_b64_e32 v[36:37], 0
	v_mov_b64_e32 v[38:39], 0
	v_mov_b64_e32 v[40:41], 0
	v_mov_b64_e32 v[42:43], 0
	v_mov_b64_e32 v[44:45], 0
	v_mov_b64_e32 v[46:47], 0
	v_mov_b64_e32 v[48:49], 0
	v_mov_b64_e32 v[50:51], 0
	v_mov_b64_e32 v[52:53], 0
	v_mov_b64_e32 v[54:55], 0
	v_mov_b64_e32 v[56:57], 0
	v_mov_b64_e32 v[58:59], 0
	v_mov_b64_e32 v[60:61], 0
	v_mov_b64_e32 v[62:63], 0
	v_mov_b64_e32 v[64:65], 0
	v_mov_b64_e32 v[66:67], 0
	v_mov_b64_e32 v[68:69], 0
	v_mov_b64_e32 v[70:71], 0
	v_mov_b64_e32 v[72:73], 0
	v_mov_b64_e32 v[74:75], 0
	v_mov_b64_e32 v[76:77], 0
	v_mov_b64_e32 v[78:79], 0
	v_mov_b64_e32 v[80:81], 0
	v_mov_b64_e32 v[82:83], 0
	v_mov_b64_e32 v[84:85], 0
	v_mov_b64_e32 v[86:87], 0
	v_mov_b64_e32 v[88:89], 0
	v_mov_b64_e32 v[90:91], 0
	v_mov_b64_e32 v[92:93], 0
	v_mov_b64_e32 v[94:95], 0
	v_mov_b64_e32 v[96:97], 0
	v_mov_b64_e32 v[98:99], 0
	v_mov_b64_e32 v[100:101], 0
	v_mov_b64_e32 v[102:103], 0
	v_mov_b64_e32 v[104:105], 0
	v_mov_b64_e32 v[106:107], 0
	v_mov_b64_e32 v[108:109], 0
	v_mov_b64_e32 v[110:111], 0
	v_mov_b64_e32 v[112:113], 0
	v_mov_b64_e32 v[114:115], 0
	v_mov_b64_e32 v[116:117], 0
	v_mov_b64_e32 v[118:119], 0
	v_mov_b64_e32 v[120:121], 0
	v_mov_b64_e32 v[122:123], 0
	v_mov_b64_e32 v[124:125], 0
	v_mov_b64_e32 v[126:127], 0
	v_mov_b64_e32 v[128:129], 0
	v_mov_b64_e32 v[130:131], 0
	v_add_u32_e32 v246, 0x10000, v144
	v_add_u32_e32 v247, 0x14000, v144
	v_add_u32_e32 v248, 0x18000, v144
	v_add_u32_e32 v249, 0x1c000, v144
	s_cmp_eq_u32 s100, 0
	s_cbranch_scc1 .Lrs5
	s_barrier
	s_mov_b32 s100, 0

.LBB0_762:
	s_add_i32 s23, s51, -2
	s_add_u32 s84, s84, 0x200080
	s_addc_u32 s85, s85, 0
	s_add_u32 s29, s86, 0x100
	s_addc_u32 s35, s87, 0
	s_mov_b32 s55, 0
	s_cmp_eq_u32 s100, 0
	s_cbranch_scc1 .Lrd6
	s_nop 15
	s_nop 15
	s_nop 15
	s_nop 15
	s_nop 15
